# v8: + conformer conv 31-tap pass: LDS reads software-pipelined (12 in flight) instead of one exposed latency per read
# speedup vs baseline: 1.0423x; 1.0042x over previous
; #define LDS_WAIT() asm volatile("s_waitcnt lgkmcnt(0)" ::: "memory")
; __device__ __forceinline__ void conv_unit_p(const bf16* __restrict__ Z, bf16* __restrict__ CAT, float* __restrict__ newc, ...
;     ...
; #pragma unroll 1
;     for (int tq = 0; tq < 32; tq += 4) {
;         float acc[4] = {bias, bias, bias, bias};
; #pragma unroll
;         for (int r = 0; r < 34; ++r) { const float gvv = gL[(tq + r) * 64 + lane];
; #pragma unroll
;             for (int q = 0; q < 4; ++q) { const int k = r - q; if (k >= 0 && k <= 30) acc[q] += wk[k] * gvv; } }
;         LDS_WAIT();
; #pragma unroll
;         for (int q = 0; q < 4; ++q) gL[(tq + q) * 64 + lane] = acc[q];
;     }
.LBB0_410:
	ds_read2st64_b32 v[136:137], v0 offset1:1
	ds_read2st64_b32 v[138:139], v0 offset0:2 offset1:3
	ds_read2st64_b32 v[140:141], v0 offset0:4 offset1:5
	ds_read2st64_b32 v[142:143], v0 offset0:6 offset1:7
	ds_read2st64_b32 v[144:145], v0 offset0:8 offset1:9
	ds_read2st64_b32 v[146:147], v0 offset0:10 offset1:11
	ds_read2st64_b32 v[148:149], v0 offset0:12 offset1:13
	ds_read2st64_b32 v[150:151], v0 offset0:14 offset1:15
	ds_read2st64_b32 v[152:153], v0 offset0:16 offset1:17
	ds_read2st64_b32 v[154:155], v0 offset0:18 offset1:19
	ds_read2st64_b32 v[156:157], v0 offset0:20 offset1:21
	ds_read2st64_b32 v[158:159], v0 offset0:22 offset1:23
	s_add_i32 s2, s2, 4
	v_add_u32_e32 v4, 0x400, v0
	s_waitcnt lgkmcnt(11)
	v_fma_f32 v1, v87, v136, v118
	v_fmac_f32_e32 v1, v88, v137
	v_fma_f32 v2, v87, v137, v118
	ds_read2st64_b32 v[160:161], v0 offset0:24 offset1:25
	s_waitcnt lgkmcnt(11)
	v_fmac_f32_e32 v1, v89, v138
	v_fmac_f32_e32 v2, v88, v138
	v_fma_f32 v3, v87, v138, v118
	v_fmac_f32_e32 v1, v90, v139
	v_fmac_f32_e32 v2, v89, v139
	v_fmac_f32_e32 v3, v88, v139
	v_fma_f32 v5, v87, v139, v118
	ds_read2st64_b32 v[162:163], v0 offset0:26 offset1:27
	s_waitcnt lgkmcnt(11)
	v_fmac_f32_e32 v1, v95, v140
	v_fmac_f32_e32 v2, v90, v140
	v_fmac_f32_e32 v3, v89, v140
	v_fmac_f32_e32 v5, v88, v140
	v_fmac_f32_e32 v1, v91, v141
	v_fmac_f32_e32 v2, v95, v141
	v_fmac_f32_e32 v3, v90, v141
	v_fmac_f32_e32 v5, v89, v141
	ds_read2st64_b32 v[164:165], v0 offset0:28 offset1:29
	s_waitcnt lgkmcnt(11)
	v_fmac_f32_e32 v1, v92, v142
	v_fmac_f32_e32 v2, v91, v142
	v_fmac_f32_e32 v3, v95, v142
	v_fmac_f32_e32 v5, v90, v142
	v_fmac_f32_e32 v1, v93, v143
	v_fmac_f32_e32 v2, v92, v143
	v_fmac_f32_e32 v3, v91, v143
	v_fmac_f32_e32 v5, v95, v143
	ds_read2st64_b32 v[166:167], v0 offset0:30 offset1:31
	s_waitcnt lgkmcnt(11)
	v_fmac_f32_e32 v1, v96, v144
	v_fmac_f32_e32 v2, v93, v144
	v_fmac_f32_e32 v3, v92, v144
	v_fmac_f32_e32 v5, v91, v144
	v_fmac_f32_e32 v1, v97, v145
	v_fmac_f32_e32 v2, v96, v145
	v_fmac_f32_e32 v3, v93, v145
	v_fmac_f32_e32 v5, v92, v145
	ds_read2st64_b32 v[188:189], v0 offset0:32 offset1:33
	s_waitcnt lgkmcnt(11)
	v_fmac_f32_e32 v1, v98, v146
	v_fmac_f32_e32 v2, v97, v146
	v_fmac_f32_e32 v3, v96, v146
	v_fmac_f32_e32 v5, v93, v146
	v_fmac_f32_e32 v1, v99, v147
	v_fmac_f32_e32 v2, v98, v147
	v_fmac_f32_e32 v3, v97, v147
	v_fmac_f32_e32 v5, v96, v147
	s_waitcnt lgkmcnt(10)
	v_fmac_f32_e32 v1, v100, v148
	v_fmac_f32_e32 v2, v99, v148
	v_fmac_f32_e32 v3, v98, v148
	v_fmac_f32_e32 v5, v97, v148
	v_fmac_f32_e32 v1, v94, v149
	v_fmac_f32_e32 v2, v100, v149
	v_fmac_f32_e32 v3, v99, v149
	v_fmac_f32_e32 v5, v98, v149
	s_waitcnt lgkmcnt(9)
	v_fmac_f32_e32 v1, v110, v150
	v_fmac_f32_e32 v2, v94, v150
	v_fmac_f32_e32 v3, v100, v150
	v_fmac_f32_e32 v5, v99, v150
	v_fmac_f32_e32 v1, v111, v151
	v_fmac_f32_e32 v2, v110, v151
	v_fmac_f32_e32 v3, v94, v151
	v_fmac_f32_e32 v5, v100, v151
	s_waitcnt lgkmcnt(8)
	v_fmac_f32_e32 v1, v101, v152
	v_fmac_f32_e32 v2, v111, v152
	v_fmac_f32_e32 v3, v110, v152
	v_fmac_f32_e32 v5, v94, v152
	v_fmac_f32_e32 v1, v102, v153
	v_fmac_f32_e32 v2, v101, v153
	v_fmac_f32_e32 v3, v111, v153
	v_fmac_f32_e32 v5, v110, v153
	s_waitcnt lgkmcnt(7)
	v_fmac_f32_e32 v1, v103, v154
	v_fmac_f32_e32 v2, v102, v154
	v_fmac_f32_e32 v3, v101, v154
	v_fmac_f32_e32 v5, v111, v154
	v_fmac_f32_e32 v1, v104, v155
	v_fmac_f32_e32 v2, v103, v155
	v_fmac_f32_e32 v3, v102, v155
	v_fmac_f32_e32 v5, v101, v155
	s_waitcnt lgkmcnt(6)
	v_fmac_f32_e32 v1, v105, v156
	v_fmac_f32_e32 v2, v104, v156
	v_fmac_f32_e32 v3, v103, v156
	v_fmac_f32_e32 v5, v102, v156
	v_fmac_f32_e32 v1, v112, v157
	v_fmac_f32_e32 v2, v105, v157
	v_fmac_f32_e32 v3, v104, v157
	v_fmac_f32_e32 v5, v103, v157
	s_waitcnt lgkmcnt(5)
	v_fmac_f32_e32 v1, v113, v158
	v_fmac_f32_e32 v2, v112, v158
	v_fmac_f32_e32 v3, v105, v158
	v_fmac_f32_e32 v5, v104, v158
	v_fmac_f32_e32 v1, v114, v159
	v_fmac_f32_e32 v2, v113, v159
	v_fmac_f32_e32 v3, v112, v159
	v_fmac_f32_e32 v5, v105, v159
	s_waitcnt lgkmcnt(4)
	v_fmac_f32_e32 v1, v106, v160
	v_fmac_f32_e32 v2, v114, v160
	v_fmac_f32_e32 v3, v113, v160
	v_fmac_f32_e32 v5, v112, v160
	v_fmac_f32_e32 v1, v107, v161
	v_fmac_f32_e32 v2, v106, v161
	v_fmac_f32_e32 v3, v114, v161
	v_fmac_f32_e32 v5, v113, v161
	s_waitcnt lgkmcnt(3)
	v_fmac_f32_e32 v1, v108, v162
	v_fmac_f32_e32 v2, v107, v162
	v_fmac_f32_e32 v3, v106, v162
	v_fmac_f32_e32 v5, v114, v162
	v_fmac_f32_e32 v1, v109, v163
	v_fmac_f32_e32 v2, v108, v163
	v_fmac_f32_e32 v3, v107, v163
	v_fmac_f32_e32 v5, v106, v163
	s_waitcnt lgkmcnt(2)
	v_fmac_f32_e32 v1, v115, v164
	v_fmac_f32_e32 v2, v109, v164
	v_fmac_f32_e32 v3, v108, v164
	v_fmac_f32_e32 v5, v107, v164
	v_fmac_f32_e32 v1, v116, v165
	v_fmac_f32_e32 v2, v115, v165
	v_fmac_f32_e32 v3, v109, v165
	v_fmac_f32_e32 v5, v108, v165
	s_waitcnt lgkmcnt(1)
	v_fmac_f32_e32 v2, v116, v166
	v_fmac_f32_e32 v3, v115, v166
	v_fmac_f32_e32 v5, v109, v166
	v_fmac_f32_e32 v1, v117, v166
	v_fmac_f32_e32 v2, v117, v167
	v_fmac_f32_e32 v3, v116, v167
	v_fmac_f32_e32 v5, v115, v167
	s_waitcnt lgkmcnt(0)
	v_fmac_f32_e32 v5, v116, v188
	v_fmac_f32_e32 v3, v117, v188
	v_fmac_f32_e32 v5, v117, v189
	s_cmp_lt_u32 s2, 28
	s_waitcnt lgkmcnt(0)
	ds_write2st64_b32 v0, v1, v2 offset1:1
	ds_write2st64_b32 v0, v3, v5 offset0:2 offset1:3
	v_mov_b32_e32 v0, v4
	s_cbranch_scc1 .LBB0_410
; #define LAS __attribute__((address_space(3)))
; __device__ __forceinline__ float sum8(float v) { v += dpp_get<0xB1, 0xF>(v); v += dpp_get<0x4E, 0xF>(v); v += dpp_get<0x141, 0xF>(v); return v; }
; __device__ __forceinline__ v4u pack8(const float (&f)[8]) { v4u w; w.x = pg8::cvt_pk_bf16(f[0], f[1]); w.y = pg8::cvt_pk_bf16(f[2], f[3]); w.z = pg8::cvt_pk_bf16(f[4], f[5]); w.w = pg8::cvt_pk_bf16(f[6], f[7]); return w; }
; __device__ __forceinline__ float sigm(float x) { return __builtin_amdgcn_rcpf(1.f + __builtin_amdgcn_exp2f(-1.44269504f * x)); }
; #define LDS_WAIT() asm volatile("s_waitcnt lgkmcnt(0)" ::: "memory")
; __device__ __forceinline__ void conv_unit_p(const bf16* __restrict__ Z, bf16* __restrict__ CAT, float* __restrict__ newc, ...
;     ...
;     LDS_WAIT();
;     float gg[8], bb[8];
; #pragma unroll
;     for (int i = 0; i < 8; ++i) { gg[i] = lg[c0 + i]; bb[i] = lb[c0 + i]; }
;     bf16* ob = CAT + (rowbase + t0) * DP + 256 + c0;
; #pragma unroll
;     for (int j = 0; j < 4; ++j) { const int r = 8 * j + rr; const f32x4 a = *(const LAS f32x4*)(gL + r * 64 + cg * 8), b = *(const LAS f32x4*)(gL + r * 64 + cg * 8 + 4);
;         float x[8] = {a[0], a[1], a[2], a[3], b[0], b[1], b[2], b[3]};
;         const float mean = sum8(((x[0] + x[1]) + (x[2] + x[3])) + ((x[4] + x[5]) + (x[6] + x[7]))) * (1.f / 64.f);
;         float q = 0.f;
; #pragma unroll
;         for (int i = 0; i < 8; ++i) { x[i] -= mean; q += x[i] * x[i]; }
;         const float rstd = rsqrtf(sum8(q) * (1.f / 64.f) + EPS);
; #pragma unroll
;         for (int i = 0; i < 8; ++i) { const float yy = x[i] * rstd * gg[i] + bb[i]; x[i] = yy * sigm(yy); }
;         *(v4u*)(ob + r * DP) = pack8(x); }
	v_mov_b64_e32 v[0:1], s[70:71]
	s_waitcnt lgkmcnt(0)
	v_mad_u64_u32 v[16:17], s[6:7], s84, v181, v[0:1]
	global_load_dwordx4 v[4:7], v128, s[54:55] offset:16
	global_load_dwordx4 v[12:15], v128, s[54:55]
	global_load_dwordx4 v[0:3], v128, s[26:27] offset:16
	global_load_dwordx4 v[8:11], v128, s[26:27]
	ds_read_b128 v[18:21], v67
	ds_read_b128 v[22:25], v67 offset:16
	s_or_b32 s4, s4, s74
	s_lshl_b64 s[4:5], s[4:5], 11
	v_lshl_add_u64 v[16:17], v[16:17], 0, s[4:5]
	s_waitcnt lgkmcnt(1)
	v_mov_b32_e32 v26, v18
	s_waitcnt lgkmcnt(0)
	v_mov_b32_e32 v27, v22
	v_mov_b32_e32 v28, v19
	v_mov_b32_e32 v29, v23
	v_pk_add_f32 v[26:27], v[26:27], v[28:29]
	v_mov_b32_e32 v28, v20
	v_mov_b32_e32 v29, v24
	v_mov_b32_e32 v30, v21
	v_mov_b32_e32 v31, v25
	v_pk_add_f32 v[28:29], v[28:29], v[30:31]
	v_mov_b32_e32 v65, v129
	v_pk_add_f32 v[26:27], v[26:27], v[28:29]
	v_lshl_add_u64 v[16:17], v[16:17], 0, v[64:65]
	v_add_f32_e32 v26, v26, v27
	s_mov_b64 s[4:5], 0x900200
	v_lshl_add_u64 v[16:17], v[16:17], 0, s[4:5]
	v_add_f32_dpp v26, v26, v26 quad_perm:[1,0,3,2] row_mask:0xf bank_mask:0xf bound_ctrl:1
	s_mov_b32 s2, 36
	v_readlane_b32 s70, v254, 58
	v_add_f32_dpp v26, v26, v26 quad_perm:[2,3,0,1] row_mask:0xf bank_mask:0xf bound_ctrl:1
	s_nop 1
	v_add_f32_dpp v26, v26, v26 row_half_mirror row_mask:0xf bank_mask:0xf bound_ctrl:1
	v_mul_f32_e32 v26, 0x3c800000, v26
	v_pk_add_f32 v[28:29], v[18:19], v[26:27] op_sel_hi:[1,0] neg_lo:[0,1] neg_hi:[0,1]
	v_pk_add_f32 v[20:21], v[20:21], v[26:27] op_sel_hi:[1,0] neg_lo:[0,1] neg_hi:[0,1]
	v_pk_mul_f32 v[30:31], v[28:29], v[28:29]
	v_pk_mul_f32 v[32:33], v[20:21], v[20:21]
	v_pk_add_f32 v[22:23], v[22:23], v[26:27] op_sel_hi:[1,0] neg_lo:[0,1] neg_hi:[0,1]
	v_pk_add_f32 v[18:19], v[24:25], v[26:27] op_sel_hi:[1,0] neg_lo:[0,1] neg_hi:[0,1]
	v_add_f32_e32 v26, v30, v31
	v_add_f32_e32 v26, v32, v26
	v_pk_mul_f32 v[34:35], v[22:23], v[22:23]
	v_add_f32_e32 v26, v33, v26
	v_add_f32_e32 v26, v34, v26
	v_pk_mul_f32 v[24:25], v[18:19], v[18:19]
	v_add_f32_e32 v26, v35, v26
	v_add_f32_e32 v24, v24, v26
	v_add_f32_e32 v24, v25, v24
	s_nop 1
	v_add_f32_dpp v24, v24, v24 quad_perm:[1,0,3,2] row_mask:0xf bank_mask:0xf bound_ctrl:1
	s_nop 1
	v_add_f32_dpp v24, v24, v24 quad_perm:[2,3,0,1] row_mask:0xf bank_mask:0xf bound_ctrl:1
	s_nop 1
	v_add_f32_dpp v24, v24, v24 row_half_mirror row_mask:0xf bank_mask:0xf bound_ctrl:1
	v_fmamk_f32 v24, v24, 0x3c800000, v168
	v_cmp_gt_f32_e32 vcc, s79, v24
	v_mul_f32_e32 v25, 0x4b800000, v24
	s_nop 0
	v_cndmask_b32_e32 v24, v24, v25, vcc
	v_rsq_f32_e32 v24, v24
	s_nop 0
	v_mul_f32_e32 v25, 0x45800000, v24
	v_cndmask_b32_e32 v24, v24, v25, vcc
	v_mul_f32_e32 v25, v28, v24
	v_mul_f32_e32 v20, v20, v24
	v_mul_f32_e32 v21, v21, v24
	v_mul_f32_e32 v22, v22, v24
	v_mul_f32_e32 v23, v23, v24
	v_mul_f32_e32 v18, v18, v24
	s_waitcnt vmcnt(1)
	v_fma_f32 v22, v4, v22, v0
	s_waitcnt vmcnt(0)
	v_fma_f32 v25, v12, v25, v8
	v_mul_f32_e32 v26, 0xbfb8aa3b, v25
	v_exp_f32_e32 v26, v26
	v_fma_f32 v20, v14, v20, v10
	v_fma_f32 v21, v15, v21, v11
	v_fma_f32 v23, v5, v23, v1
	v_add_f32_e32 v26, 1.0, v26
	v_rcp_f32_e32 v26, v26
	v_fma_f32 v18, v6, v18, v2
	v_mul_f32_e32 v25, v25, v26
	v_mul_f32_e32 v26, v29, v24
	v_fma_f32 v26, v13, v26, v9
	v_mul_f32_e32 v27, 0xbfb8aa3b, v26
	v_exp_f32_e32 v27, v27
	s_nop 0
	v_add_f32_e32 v27, 1.0, v27
	v_rcp_f32_e32 v27, v27
	s_nop 0
	v_mul_f32_e32 v26, v26, v27
	v_mul_f32_e32 v27, 0xbfb8aa3b, v20
	v_exp_f32_e32 v27, v27
	s_nop 0
	v_add_f32_e32 v27, 1.0, v27
	v_rcp_f32_e32 v27, v27
	s_nop 0
	v_mul_f32_e32 v20, v20, v27
	v_mul_f32_e32 v27, 0xbfb8aa3b, v21
	v_exp_f32_e32 v27, v27
	s_nop 0
	v_add_f32_e32 v27, 1.0, v27
	v_rcp_f32_e32 v27, v27
	s_nop 0
	v_mul_f32_e32 v21, v21, v27
	v_mul_f32_e32 v27, 0xbfb8aa3b, v22
	v_exp_f32_e32 v27, v27
	s_nop 0
	v_add_f32_e32 v27, 1.0, v27
	v_rcp_f32_e32 v27, v27
	s_nop 0
	v_mul_f32_e32 v22, v22, v27
	v_mul_f32_e32 v27, 0xbfb8aa3b, v23
	v_exp_f32_e32 v27, v27
	s_nop 0
	v_add_f32_e32 v27, 1.0, v27
	v_rcp_f32_e32 v27, v27
	s_nop 0
	v_mul_f32_e32 v23, v23, v27
	v_mul_f32_e32 v27, 0xbfb8aa3b, v18
	v_exp_f32_e32 v27, v27
	s_nop 0
	v_add_f32_e32 v27, 1.0, v27
	v_rcp_f32_e32 v27, v27
	s_nop 0
	v_mul_f32_e32 v27, v18, v27
	v_mul_f32_e32 v18, v19, v24
	v_fma_f32 v18, v7, v18, v3
	v_mul_f32_e32 v19, 0xbfb8aa3b, v18
	v_exp_f32_e32 v19, v19
	s_nop 0
	v_add_f32_e32 v19, 1.0, v19
	v_rcp_f32_e32 v19, v19
	s_nop 0
	v_mul_f32_e32 v24, v18, v19
	v_cvt_pk_bf16_f32 v18, v25, v26
	v_cvt_pk_bf16_f32 v19, v20, v21
	v_cvt_pk_bf16_f32 v20, v22, v23
	v_lshlrev_b32_e32 v22, 10, v86
	v_ashrrev_i32_e32 v23, 31, v22
	v_lshl_add_u64 v[22:23], v[22:23], 1, v[16:17]
	v_cvt_pk_bf16_f32 v21, v27, v24
	global_store_dwordx4 v[22:23], v[18:21], off
	ds_read_b128 v[18:21], v56
	ds_read_b128 v[22:25], v56 offset:16
	s_waitcnt lgkmcnt(1)
	v_mov_b32_e32 v26, v18
	s_waitcnt lgkmcnt(0)
; #define LAS __attribute__((address_space(3)))
; __device__ __forceinline__ float sum8(float v) { v += dpp_get<0xB1, 0xF>(v); v += dpp_get<0x4E, 0xF>(v); v += dpp_get<0x141, 0xF>(v); return v; }
; __device__ __forceinline__ v4u pack8(const float (&f)[8]) { v4u w; w.x = pg8::cvt_pk_bf16(f[0], f[1]); w.y = pg8::cvt_pk_bf16(f[2], f[3]); w.z = pg8::cvt_pk_bf16(f[4], f[5]); w.w = pg8::cvt_pk_bf16(f[6], f[7]); return w; }
; __device__ __forceinline__ float sigm(float x) { return __builtin_amdgcn_rcpf(1.f + __builtin_amdgcn_exp2f(-1.44269504f * x)); }
; __device__ __forceinline__ void conv_unit_p(const bf16* __restrict__ Z, bf16* __restrict__ CAT, float* __restrict__ newc, ...
;     ...
; #pragma unroll
;     for (int j = 0; j < 4; ++j) { const int r = 8 * j + rr; const f32x4 a = *(const LAS f32x4*)(gL + r * 64 + cg * 8), b = *(const LAS f32x4*)(gL + r * 64 + cg * 8 + 4);
;         float x[8] = {a[0], a[1], a[2], a[3], b[0], b[1], b[2], b[3]};
;         const float mean = sum8(((x[0] + x[1]) + (x[2] + x[3])) + ((x[4] + x[5]) + (x[6] + x[7]))) * (1.f / 64.f);
;         float q = 0.f;
; #pragma unroll
;         for (int i = 0; i < 8; ++i) { x[i] -= mean; q += x[i] * x[i]; }
;         const float rstd = rsqrtf(sum8(q) * (1.f / 64.f) + EPS);
; #pragma unroll
;         for (int i = 0; i < 8; ++i) { const float yy = x[i] * rstd * gg[i] + bb[i]; x[i] = yy * sigm(yy); }
;         *(v4u*)(ob + r * DP) = pack8(x); }
	v_mov_b32_e32 v27, v22
	v_mov_b32_e32 v28, v19
	v_mov_b32_e32 v29, v23
	v_pk_add_f32 v[26:27], v[26:27], v[28:29]
	v_mov_b32_e32 v28, v20
	v_mov_b32_e32 v29, v24
	v_mov_b32_e32 v30, v21
	v_mov_b32_e32 v31, v25
	v_pk_add_f32 v[28:29], v[28:29], v[30:31]
	s_nop 0
	v_pk_add_f32 v[26:27], v[26:27], v[28:29]
	s_nop 0
	v_add_f32_e32 v26, v26, v27
	s_nop 1
	v_add_f32_dpp v26, v26, v26 quad_perm:[1,0,3,2] row_mask:0xf bank_mask:0xf bound_ctrl:1
	s_nop 1
	v_add_f32_dpp v26, v26, v26 quad_perm:[2,3,0,1] row_mask:0xf bank_mask:0xf bound_ctrl:1
	s_nop 1
	v_add_f32_dpp v26, v26, v26 row_half_mirror row_mask:0xf bank_mask:0xf bound_ctrl:1
	v_mul_f32_e32 v26, 0x3c800000, v26
	v_pk_add_f32 v[18:19], v[18:19], v[26:27] op_sel_hi:[1,0] neg_lo:[0,1] neg_hi:[0,1]
	v_pk_add_f32 v[20:21], v[20:21], v[26:27] op_sel_hi:[1,0] neg_lo:[0,1] neg_hi:[0,1]
	v_pk_mul_f32 v[28:29], v[18:19], v[18:19]
	v_pk_mul_f32 v[30:31], v[20:21], v[20:21]
	v_add_f32_e32 v28, v28, v29
	v_pk_add_f32 v[22:23], v[22:23], v[26:27] op_sel_hi:[1,0] neg_lo:[0,1] neg_hi:[0,1]
	v_add_f32_e32 v28, v30, v28
	v_pk_mul_f32 v[32:33], v[22:23], v[22:23]
	v_add_f32_e32 v28, v31, v28
	v_pk_add_f32 v[24:25], v[24:25], v[26:27] op_sel_hi:[1,0] neg_lo:[0,1] neg_hi:[0,1]
	v_add_f32_e32 v28, v32, v28
	v_pk_mul_f32 v[26:27], v[24:25], v[24:25]
	v_add_f32_e32 v28, v33, v28
	v_add_f32_e32 v26, v26, v28
	v_add_f32_e32 v26, v27, v26
	s_nop 1
	v_add_f32_dpp v26, v26, v26 quad_perm:[1,0,3,2] row_mask:0xf bank_mask:0xf bound_ctrl:1
	s_nop 1
	v_add_f32_dpp v26, v26, v26 quad_perm:[2,3,0,1] row_mask:0xf bank_mask:0xf bound_ctrl:1
	s_nop 1
	v_add_f32_dpp v26, v26, v26 row_half_mirror row_mask:0xf bank_mask:0xf bound_ctrl:1
	v_fmamk_f32 v26, v26, 0x3c800000, v168
	v_cmp_gt_f32_e32 vcc, s79, v26
	v_mul_f32_e32 v27, 0x4b800000, v26
	s_nop 0
	v_cndmask_b32_e32 v26, v26, v27, vcc
	v_rsq_f32_e32 v26, v26
	s_nop 0
	v_mul_f32_e32 v27, 0x45800000, v26
	v_cndmask_b32_e32 v26, v26, v27, vcc
	v_mul_f32_e32 v18, v18, v26
	v_fma_f32 v18, v12, v18, v8
	v_mul_f32_e32 v27, 0xbfb8aa3b, v18
	v_exp_f32_e32 v27, v27
	v_mul_f32_e32 v19, v19, v26
	v_fma_f32 v19, v13, v19, v9
	v_mul_f32_e32 v20, v20, v26
	v_add_f32_e32 v27, 1.0, v27
	v_rcp_f32_e32 v27, v27
	v_fma_f32 v20, v14, v20, v10
	v_mul_f32_e32 v21, v21, v26
	v_fma_f32 v21, v15, v21, v11
	v_mul_f32_e32 v18, v18, v27
	v_mul_f32_e32 v27, 0xbfb8aa3b, v19
	v_exp_f32_e32 v27, v27
	v_mul_f32_e32 v22, v22, v26
	v_fma_f32 v22, v4, v22, v0
	v_mul_f32_e32 v23, v23, v26
	v_add_f32_e32 v27, 1.0, v27
	v_rcp_f32_e32 v27, v27
	v_fma_f32 v23, v5, v23, v1
	v_mul_f32_e32 v24, v24, v26
	v_mul_f32_e32 v25, v25, v26
	v_mul_f32_e32 v19, v19, v27
	v_mul_f32_e32 v27, 0xbfb8aa3b, v20
	v_exp_f32_e32 v27, v27
	v_fma_f32 v24, v6, v24, v2
	v_fma_f32 v25, v7, v25, v3
	v_mul_f32_e32 v26, 0xbfb8aa3b, v25
	v_add_f32_e32 v27, 1.0, v27
	v_rcp_f32_e32 v27, v27
	v_exp_f32_e32 v26, v26
	v_cvt_pk_bf16_f32 v18, v18, v19
	v_mul_f32_e32 v20, v20, v27
	v_mul_f32_e32 v27, 0xbfb8aa3b, v21
	v_exp_f32_e32 v27, v27
	v_add_f32_e32 v26, 1.0, v26
	v_rcp_f32_e32 v26, v26
	v_add_f32_e32 v27, 1.0, v27
	v_rcp_f32_e32 v27, v27
	v_mul_f32_e32 v25, v25, v26
	v_mul_f32_e32 v21, v21, v27
	v_mul_f32_e32 v27, 0xbfb8aa3b, v22
	v_exp_f32_e32 v27, v27
	v_cvt_pk_bf16_f32 v19, v20, v21
	s_nop 0
	v_add_f32_e32 v27, 1.0, v27
	v_rcp_f32_e32 v27, v27
	s_nop 0
	v_mul_f32_e32 v22, v22, v27
	v_mul_f32_e32 v27, 0xbfb8aa3b, v23
	v_exp_f32_e32 v27, v27
	s_nop 0
	v_add_f32_e32 v27, 1.0, v27
	v_rcp_f32_e32 v27, v27
	s_nop 0
	v_mul_f32_e32 v23, v23, v27
	v_mul_f32_e32 v27, 0xbfb8aa3b, v24
	v_exp_f32_e32 v27, v27
	v_cvt_pk_bf16_f32 v20, v22, v23
	v_lshlrev_b32_e32 v22, 10, v85
	v_ashrrev_i32_e32 v23, 31, v22
	v_add_f32_e32 v27, 1.0, v27
	v_rcp_f32_e32 v27, v27
	v_lshl_add_u64 v[22:23], v[22:23], 1, v[16:17]
	v_mul_f32_e32 v24, v24, v27
	v_cvt_pk_bf16_f32 v21, v24, v25
	global_store_dwordx4 v[22:23], v[18:21], off
	ds_read_b128 v[18:21], v48
	ds_read_b128 v[22:25], v48 offset:16
	s_waitcnt lgkmcnt(1)
	v_mov_b32_e32 v26, v18
	s_waitcnt lgkmcnt(0)
	v_mov_b32_e32 v27, v22
	v_mov_b32_e32 v28, v19
	v_mov_b32_e32 v29, v23
	v_pk_add_f32 v[26:27], v[26:27], v[28:29]
	v_mov_b32_e32 v28, v20
	v_mov_b32_e32 v29, v24
	v_mov_b32_e32 v30, v21
	v_mov_b32_e32 v31, v25
	v_pk_add_f32 v[28:29], v[28:29], v[30:31]
	s_nop 0
	v_pk_add_f32 v[26:27], v[26:27], v[28:29]
	s_nop 0
	v_add_f32_e32 v26, v26, v27
	s_nop 1
	v_add_f32_dpp v26, v26, v26 quad_perm:[1,0,3,2] row_mask:0xf bank_mask:0xf bound_ctrl:1
	s_nop 1
	v_add_f32_dpp v26, v26, v26 quad_perm:[2,3,0,1] row_mask:0xf bank_mask:0xf bound_ctrl:1
	s_nop 1
	v_add_f32_dpp v26, v26, v26 row_half_mirror row_mask:0xf bank_mask:0xf bound_ctrl:1
	v_mul_f32_e32 v26, 0x3c800000, v26
	v_pk_add_f32 v[18:19], v[18:19], v[26:27] op_sel_hi:[1,0] neg_lo:[0,1] neg_hi:[0,1]
	v_pk_add_f32 v[20:21], v[20:21], v[26:27] op_sel_hi:[1,0] neg_lo:[0,1] neg_hi:[0,1]
	v_pk_mul_f32 v[28:29], v[18:19], v[18:19]
	v_pk_mul_f32 v[30:31], v[20:21], v[20:21]
	v_add_f32_e32 v28, v28, v29
	v_pk_add_f32 v[22:23], v[22:23], v[26:27] op_sel_hi:[1,0] neg_lo:[0,1] neg_hi:[0,1]
	v_add_f32_e32 v28, v30, v28
	v_pk_mul_f32 v[32:33], v[22:23], v[22:23]
	v_add_f32_e32 v28, v31, v28
	v_pk_add_f32 v[24:25], v[24:25], v[26:27] op_sel_hi:[1,0] neg_lo:[0,1] neg_hi:[0,1]
	v_add_f32_e32 v28, v32, v28
	v_pk_mul_f32 v[26:27], v[24:25], v[24:25]
	v_add_f32_e32 v28, v33, v28
	v_add_f32_e32 v26, v26, v28
	v_add_f32_e32 v26, v27, v26
	s_nop 1
	v_add_f32_dpp v26, v26, v26 quad_perm:[1,0,3,2] row_mask:0xf bank_mask:0xf bound_ctrl:1
	s_nop 1
	v_add_f32_dpp v26, v26, v26 quad_perm:[2,3,0,1] row_mask:0xf bank_mask:0xf bound_ctrl:1
	s_nop 1
	v_add_f32_dpp v26, v26, v26 row_half_mirror row_mask:0xf bank_mask:0xf bound_ctrl:1
; #define LAS __attribute__((address_space(3)))
; __device__ __forceinline__ float sum8(float v) { v += dpp_get<0xB1, 0xF>(v); v += dpp_get<0x4E, 0xF>(v); v += dpp_get<0x141, 0xF>(v); return v; }
; __device__ __forceinline__ v4u pack8(const float (&f)[8]) { v4u w; w.x = pg8::cvt_pk_bf16(f[0], f[1]); w.y = pg8::cvt_pk_bf16(f[2], f[3]); w.z = pg8::cvt_pk_bf16(f[4], f[5]); w.w = pg8::cvt_pk_bf16(f[6], f[7]); return w; }
; __device__ __forceinline__ float sigm(float x) { return __builtin_amdgcn_rcpf(1.f + __builtin_amdgcn_exp2f(-1.44269504f * x)); }
; #define LDS_WAIT() asm volatile("s_waitcnt lgkmcnt(0)" ::: "memory")
; __device__ __forceinline__ void conv_unit_p(const bf16* __restrict__ Z, bf16* __restrict__ CAT, float* __restrict__ newc, ...
;     ...
; #pragma unroll
;     for (int j = 0; j < 4; ++j) { const int r = 8 * j + rr; const f32x4 a = *(const LAS f32x4*)(gL + r * 64 + cg * 8), b = *(const LAS f32x4*)(gL + r * 64 + cg * 8 + 4);
;         float x[8] = {a[0], a[1], a[2], a[3], b[0], b[1], b[2], b[3]};
;         const float mean = sum8(((x[0] + x[1]) + (x[2] + x[3])) + ((x[4] + x[5]) + (x[6] + x[7]))) * (1.f / 64.f);
;         float q = 0.f;
; #pragma unroll
;         for (int i = 0; i < 8; ++i) { x[i] -= mean; q += x[i] * x[i]; }
;         const float rstd = rsqrtf(sum8(q) * (1.f / 64.f) + EPS);
; #pragma unroll
;         for (int i = 0; i < 8; ++i) { const float yy = x[i] * rstd * gg[i] + bb[i]; x[i] = yy * sigm(yy); }
;         *(v4u*)(ob + r * DP) = pack8(x); }
;     LDS_WAIT();
	v_fmamk_f32 v26, v26, 0x3c800000, v168
	v_cmp_gt_f32_e32 vcc, s79, v26
	v_mul_f32_e32 v27, 0x4b800000, v26
	s_nop 0
	v_cndmask_b32_e32 v26, v26, v27, vcc
	v_rsq_f32_e32 v26, v26
	s_nop 0
	v_mul_f32_e32 v27, 0x45800000, v26
	v_cndmask_b32_e32 v26, v26, v27, vcc
	v_mul_f32_e32 v18, v18, v26
	v_fma_f32 v18, v12, v18, v8
	v_mul_f32_e32 v27, 0xbfb8aa3b, v18
	v_exp_f32_e32 v27, v27
	v_mul_f32_e32 v19, v19, v26
	v_fma_f32 v19, v13, v19, v9
	v_mul_f32_e32 v20, v20, v26
	v_add_f32_e32 v27, 1.0, v27
	v_rcp_f32_e32 v27, v27
	v_fma_f32 v20, v14, v20, v10
	v_mul_f32_e32 v21, v21, v26
	v_fma_f32 v21, v15, v21, v11
	v_mul_f32_e32 v18, v18, v27
	v_mul_f32_e32 v27, 0xbfb8aa3b, v19
	v_exp_f32_e32 v27, v27
	v_mul_f32_e32 v22, v22, v26
	v_fma_f32 v22, v4, v22, v0
	v_mul_f32_e32 v23, v23, v26
	v_add_f32_e32 v27, 1.0, v27
	v_rcp_f32_e32 v27, v27
	v_fma_f32 v23, v5, v23, v1
	v_mul_f32_e32 v24, v24, v26
	v_mul_f32_e32 v25, v25, v26
	v_mul_f32_e32 v19, v19, v27
	v_mul_f32_e32 v27, 0xbfb8aa3b, v20
	v_exp_f32_e32 v27, v27
	v_fma_f32 v24, v6, v24, v2
	v_fma_f32 v25, v7, v25, v3
	v_mul_f32_e32 v26, 0xbfb8aa3b, v25
	v_add_f32_e32 v27, 1.0, v27
	v_rcp_f32_e32 v27, v27
	v_exp_f32_e32 v26, v26
	v_cvt_pk_bf16_f32 v18, v18, v19
	v_mul_f32_e32 v20, v20, v27
	v_mul_f32_e32 v27, 0xbfb8aa3b, v21
	v_exp_f32_e32 v27, v27
	v_add_f32_e32 v26, 1.0, v26
	v_rcp_f32_e32 v26, v26
	v_add_f32_e32 v27, 1.0, v27
	v_rcp_f32_e32 v27, v27
	v_mul_f32_e32 v25, v25, v26
	v_mul_f32_e32 v21, v21, v27
	v_mul_f32_e32 v27, 0xbfb8aa3b, v22
	v_exp_f32_e32 v27, v27
	v_cvt_pk_bf16_f32 v19, v20, v21
	s_nop 0
	v_add_f32_e32 v27, 1.0, v27
	v_rcp_f32_e32 v27, v27
	s_nop 0
	v_mul_f32_e32 v22, v22, v27
	v_mul_f32_e32 v27, 0xbfb8aa3b, v23
	v_exp_f32_e32 v27, v27
	s_nop 0
	v_add_f32_e32 v27, 1.0, v27
	v_rcp_f32_e32 v27, v27
	s_nop 0
	v_mul_f32_e32 v23, v23, v27
	v_mul_f32_e32 v27, 0xbfb8aa3b, v24
	v_exp_f32_e32 v27, v27
	v_cvt_pk_bf16_f32 v20, v22, v23
	v_lshlrev_b32_e32 v22, 10, v83
	v_ashrrev_i32_e32 v23, 31, v22
	v_add_f32_e32 v27, 1.0, v27
	v_rcp_f32_e32 v27, v27
	v_lshl_add_u64 v[22:23], v[22:23], 1, v[16:17]
	v_mul_f32_e32 v24, v24, v27
	v_cvt_pk_bf16_f32 v21, v24, v25
	global_store_dwordx4 v[22:23], v[18:21], off
	ds_read_b128 v[18:21], v40
	ds_read_b128 v[22:25], v40 offset:16
	s_waitcnt lgkmcnt(1)
	v_mov_b32_e32 v26, v18
	s_waitcnt lgkmcnt(0)
	v_mov_b32_e32 v27, v22
	v_mov_b32_e32 v28, v19
	v_mov_b32_e32 v29, v23
	v_pk_add_f32 v[26:27], v[26:27], v[28:29]
	v_mov_b32_e32 v28, v20
	v_mov_b32_e32 v29, v24
	v_mov_b32_e32 v30, v21
	v_mov_b32_e32 v31, v25
	v_pk_add_f32 v[28:29], v[28:29], v[30:31]
	s_nop 0
	v_pk_add_f32 v[26:27], v[26:27], v[28:29]
	s_nop 0
	v_add_f32_e32 v26, v26, v27
	s_nop 1
	v_add_f32_dpp v26, v26, v26 quad_perm:[1,0,3,2] row_mask:0xf bank_mask:0xf bound_ctrl:1
	s_nop 1
	v_add_f32_dpp v26, v26, v26 quad_perm:[2,3,0,1] row_mask:0xf bank_mask:0xf bound_ctrl:1
	s_nop 1
	v_add_f32_dpp v26, v26, v26 row_half_mirror row_mask:0xf bank_mask:0xf bound_ctrl:1
	v_mul_f32_e32 v26, 0x3c800000, v26
	v_pk_add_f32 v[18:19], v[18:19], v[26:27] op_sel_hi:[1,0] neg_lo:[0,1] neg_hi:[0,1]
	v_pk_add_f32 v[20:21], v[20:21], v[26:27] op_sel_hi:[1,0] neg_lo:[0,1] neg_hi:[0,1]
	v_pk_mul_f32 v[28:29], v[18:19], v[18:19]
	v_pk_mul_f32 v[30:31], v[20:21], v[20:21]
	v_add_f32_e32 v28, v28, v29
	v_pk_add_f32 v[22:23], v[22:23], v[26:27] op_sel_hi:[1,0] neg_lo:[0,1] neg_hi:[0,1]
	v_add_f32_e32 v28, v30, v28
	v_pk_mul_f32 v[32:33], v[22:23], v[22:23]
	v_add_f32_e32 v28, v31, v28
	v_pk_add_f32 v[24:25], v[24:25], v[26:27] op_sel_hi:[1,0] neg_lo:[0,1] neg_hi:[0,1]
	v_add_f32_e32 v28, v32, v28
	v_pk_mul_f32 v[26:27], v[24:25], v[24:25]
	v_add_f32_e32 v28, v33, v28
	v_add_f32_e32 v26, v26, v28
	v_add_f32_e32 v26, v27, v26
	s_nop 1
	v_add_f32_dpp v26, v26, v26 quad_perm:[1,0,3,2] row_mask:0xf bank_mask:0xf bound_ctrl:1
	s_nop 1
	v_add_f32_dpp v26, v26, v26 quad_perm:[2,3,0,1] row_mask:0xf bank_mask:0xf bound_ctrl:1
	s_nop 1
	v_add_f32_dpp v26, v26, v26 row_half_mirror row_mask:0xf bank_mask:0xf bound_ctrl:1
	v_fmamk_f32 v26, v26, 0x3c800000, v168
	v_cmp_gt_f32_e32 vcc, s79, v26
	v_mul_f32_e32 v27, 0x4b800000, v26
	s_nop 0
	v_cndmask_b32_e32 v26, v26, v27, vcc
	v_rsq_f32_e32 v26, v26
	s_nop 0
	v_mul_f32_e32 v27, 0x45800000, v26
	v_cndmask_b32_e32 v26, v26, v27, vcc
	v_mul_f32_e32 v18, v18, v26
	v_fma_f32 v8, v12, v18, v8
	v_mul_f32_e32 v12, 0xbfb8aa3b, v8
	v_exp_f32_e32 v12, v12
	s_nop 0
	v_add_f32_e32 v12, 1.0, v12
	v_rcp_f32_e32 v12, v12
	s_nop 0
	v_mul_f32_e32 v8, v8, v12
	v_mul_f32_e32 v12, v19, v26
	v_fma_f32 v9, v13, v12, v9
	v_mul_f32_e32 v12, 0xbfb8aa3b, v9
	v_exp_f32_e32 v12, v12
	s_nop 0
	v_add_f32_e32 v12, 1.0, v12
	v_rcp_f32_e32 v12, v12
	s_nop 0
	v_mul_f32_e32 v9, v9, v12
	v_mul_f32_e32 v12, v20, v26
	v_fma_f32 v10, v14, v12, v10
	v_mul_f32_e32 v12, 0xbfb8aa3b, v10
	v_exp_f32_e32 v12, v12
	s_nop 0
	v_add_f32_e32 v12, 1.0, v12
	v_rcp_f32_e32 v12, v12
	s_nop 0
	v_mul_f32_e32 v10, v10, v12
	v_mul_f32_e32 v12, v21, v26
	v_fmac_f32_e32 v11, v15, v12
	v_mul_f32_e32 v12, 0xbfb8aa3b, v11
	v_exp_f32_e32 v12, v12
	s_nop 0
	v_add_f32_e32 v12, 1.0, v12
	v_rcp_f32_e32 v12, v12
	s_nop 0
	v_mul_f32_e32 v11, v11, v12
	v_mul_f32_e32 v12, v22, v26
	v_fma_f32 v0, v4, v12, v0
	v_mul_f32_e32 v4, 0xbfb8aa3b, v0
	v_exp_f32_e32 v4, v4
	s_nop 0
	v_add_f32_e32 v4, 1.0, v4
	v_rcp_f32_e32 v4, v4
	s_nop 0
	v_mul_f32_e32 v4, v0, v4
	v_mul_f32_e32 v0, v23, v26
	v_fma_f32 v0, v5, v0, v1
	v_mul_f32_e32 v1, 0xbfb8aa3b, v0
	v_exp_f32_e32 v1, v1
	s_nop 0
	v_add_f32_e32 v1, 1.0, v1
	v_rcp_f32_e32 v1, v1
	s_nop 0
	v_mul_f32_e32 v5, v0, v1
	v_mul_f32_e32 v0, v24, v26
	v_fma_f32 v0, v6, v0, v2
	v_mul_f32_e32 v1, 0xbfb8aa3b, v0
	v_exp_f32_e32 v1, v1
	s_nop 0
	v_add_f32_e32 v1, 1.0, v1
	v_rcp_f32_e32 v1, v1
	s_nop 0
	v_mul_f32_e32 v6, v0, v1
	v_mul_f32_e32 v0, v25, v26
	v_fmac_f32_e32 v3, v7, v0
	v_mul_f32_e32 v0, 0xbfb8aa3b, v3
	v_exp_f32_e32 v0, v0
	s_nop 0
	v_add_f32_e32 v0, 1.0, v0
	v_rcp_f32_e32 v0, v0
	s_nop 0
	v_mul_f32_e32 v3, v3, v0
	v_cvt_pk_bf16_f32 v0, v8, v9
	v_cvt_pk_bf16_f32 v1, v10, v11
	v_cvt_pk_bf16_f32 v2, v4, v5
	v_lshlrev_b32_e32 v4, 10, v81
	v_ashrrev_i32_e32 v5, 31, v4
	v_lshl_add_u64 v[4:5], v[4:5], 1, v[16:17]
	v_cvt_pk_bf16_f32 v3, v6, v3
	global_store_dwordx4 v[4:5], v[0:3], off
	s_waitcnt lgkmcnt(0)
